# stack + 32-bit tile offsets in the attention DMA hooks + no vmcnt(0) drain in front of the unit's first QK MFMA
# speedup vs baseline: 1.0028x; 1.0028x over previous
.LBB0_449:
	s_lshl_b32 s2, s48, 1
	s_sub_i32 s39, s2, s33
	s_add_i32 s3, s7, 0x2000
	s_or_b32 s2, s34, 64
	s_lshl_b32 s60, s33, 6
	s_add_i32 s5, s60, 0x80
	s_cmp_gt_i32 s39, 0
	s_cselect_b32 s62, s60, s5
	s_ashr_i32 s63, s62, 31
	s_lshl_b64 s[62:63], s[62:63], 12
	v_lshl_add_u64 v[2:3], v[202:203], 0, s[62:63]
	v_lshl_add_u64 v[6:7], v[2:3], 0, s[30:31]
	s_mov_b32 m0, s50
	v_lshl_add_u64 v[2:3], v[2:3], 0, s[36:37]
	global_load_lds_dwordx4 v[6:7], off
	s_mov_b32 m0, s51
	v_add_u32_e32 v35, v218, v149
	global_load_lds_dwordx4 v[2:3], off
	s_waitcnt vmcnt(6) lgkmcnt(0)
	s_barrier
	ds_read_b128 v[18:21], v35
	ds_read_b128 v[36:39], v35 offset:4096
	v_and_b32_e32 v155, 0x7fffffff, v1
	v_mov_b32_e32 v0, v201
	v_pk_mul_f32 v[16:17], v[170:171], v[0:1] op_sel_hi:[1,0] neg_lo:[0,1] neg_hi:[0,1]
	v_pk_mul_f32 v[14:15], v[168:169], v[0:1] op_sel_hi:[1,0] neg_lo:[0,1] neg_hi:[0,1]
	v_pk_mul_f32 v[12:13], v[166:167], v[0:1] op_sel_hi:[1,0] neg_lo:[0,1] neg_hi:[0,1]
	v_pk_mul_f32 v[10:11], v[164:165], v[0:1] op_sel_hi:[1,0] neg_lo:[0,1] neg_hi:[0,1]
	v_pk_mul_f32 v[8:9], v[162:163], v[0:1] op_sel_hi:[1,0] neg_lo:[0,1] neg_hi:[0,1]
	v_pk_mul_f32 v[6:7], v[158:159], v[0:1] op_sel_hi:[1,0] neg_lo:[0,1] neg_hi:[0,1]
	v_pk_mul_f32 v[4:5], v[156:157], v[0:1] op_sel_hi:[1,0] neg_lo:[0,1] neg_hi:[0,1]
	v_pk_mul_f32 v[2:3], v[154:155], v[0:1] op_sel_hi:[1,0] neg_lo:[0,1] neg_hi:[0,1]
	v_pk_mul_f32 v[32:33], v[192:193], v[0:1] op_sel_hi:[1,0] neg_lo:[0,1] neg_hi:[0,1]
	v_pk_mul_f32 v[30:31], v[190:191], v[0:1] op_sel_hi:[1,0] neg_lo:[0,1] neg_hi:[0,1]
	s_waitcnt lgkmcnt(0)
	v_mfma_f32_32x32x16_bf16 v[2:17], v[18:21], v[130:133], v[2:17]
	v_mul_f32_e64 v28, v188, -v0
	v_mul_f32_e64 v29, v189, -v0
	v_mul_f32_e64 v26, v186, -v0
	v_mul_f32_e64 v27, v187, -v0
	v_mul_f32_e64 v24, v184, -v0
	v_mul_f32_e64 v25, v185, -v0
	v_pk_mul_f32 v[22:23], v[176:177], v[0:1] op_sel_hi:[1,0] neg_lo:[0,1] neg_hi:[0,1]
	v_pk_mul_f32 v[20:21], v[174:175], v[0:1] op_sel_hi:[1,0] neg_lo:[0,1] neg_hi:[0,1]
	v_pk_mul_f32 v[18:19], v[172:173], v[0:1] op_sel_hi:[1,0] neg_lo:[0,1] neg_hi:[0,1]
	v_add_u32_e32 v48, v218, v208
	v_add_u32_e32 v49, v218, v209
	v_mfma_f32_32x32x16_bf16 v[18:33], v[36:39], v[130:133], v[18:33]
	ds_read_b128 v[36:39], v48
	ds_read_b128 v[40:43], v48 offset:4096
	v_add_u32_e32 v50, v218, v226
	s_sub_i32 s48, s4, s33
	s_cmp_gt_i32 s39, 1
	s_cselect_b32 s4, 1, 3
	s_add_i32 s4, s4, s33
	s_lshl_b32 s4, s4, 6
	s_waitcnt lgkmcnt(1)
	v_mfma_f32_32x32x16_bf16 v[2:17], v[36:39], v[134:137], v[2:17]
	s_ashr_i32 s5, s4, 31
	s_lshl_b64 s[4:5], s[4:5], 12
	s_mov_b32 m0, s7
	s_mov_b32 s10, 0
	s_waitcnt lgkmcnt(0)
	v_mfma_f32_32x32x16_bf16 v[18:33], v[40:43], v[134:137], v[18:33]
	ds_read_b128 v[36:39], v49
	ds_read_b128 v[40:43], v49 offset:4096
	s_waitcnt lgkmcnt(1)
	v_mfma_f32_32x32x16_bf16 v[2:17], v[36:39], v[138:141], v[2:17]
	ds_read_b128 v[36:39], v50
	s_waitcnt lgkmcnt(1)
	v_mfma_f32_32x32x16_bf16 v[18:33], v[40:43], v[138:141], v[18:33]
	ds_read_b128 v[40:43], v50 offset:4096
	s_waitcnt vmcnt(4) lgkmcnt(0)
	s_barrier
	s_waitcnt lgkmcnt(1)
	v_mfma_f32_32x32x16_bf16 v[2:17], v[36:39], v[142:145], v[2:17]
	v_lshl_add_u64 v[36:37], v[202:203], 0, s[4:5]
	v_lshl_add_u64 v[38:39], v[36:37], 0, s[30:31]
	global_load_lds_dwordx4 v[38:39], off
	v_lshl_add_u64 v[36:37], v[36:37], 0, s[36:37]
	s_mov_b32 m0, s3
	v_or_b32_e32 v38, s2, v148
	global_load_lds_dwordx4 v[36:37], off
	v_lshl_add_u64 v[36:37], v[44:45], 0, s[40:41]
	s_mov_b32 m0, s54
	s_waitcnt lgkmcnt(0)
	v_mfma_f32_32x32x16_bf16 v[18:33], v[40:43], v[142:145], v[18:33]
	global_load_lds_dwordx4 v[36:37], off
	v_lshl_add_u64 v[36:37], v[46:47], 0, s[40:41]
	s_mov_b32 m0, s55
	s_nop 0
	global_load_lds_dwordx4 v[36:37], off
	v_max3_f32 v36, v2, v3, v18
	v_max3_f32 v37, v4, v5, v19
	s_nop 15
	s_nop 15
	s_nop 15
	s_nop 0
	v_max3_f32 v36, v36, v20, v21
	v_max3_f32 v37, v37, v8, v9
	s_nop 0
	v_max3_f32 v36, v36, v6, v7
	v_max3_f32 v37, v37, v24, v25
	s_nop 0
	v_max3_f32 v36, v36, v22, v23
	v_max3_f32 v37, v37, v12, v13
	s_nop 0
	v_max3_f32 v36, v36, v10, v11
	v_max3_f32 v37, v37, v28, v29
	s_nop 0
	v_max3_f32 v36, v36, v26, v27
	v_max3_f32 v37, v37, v16, v17
	s_nop 0
	v_max3_f32 v36, v36, v14, v15
	v_max3_f32 v37, v37, v32, v33
	s_nop 0
	v_max3_f32 v36, v36, v30, v31
	s_nop 0
	v_max_f32_e32 v36, v36, v37
	s_nop 0
	v_mov_b32_e32 v37, v36
	s_nop 1
	v_permlane32_swap_b32 v36, v37
	s_nop 1
	s_nop 0
	v_max_f32_e32 v37, v37, v37
	v_max_f32_e32 v36, v36, v36
	v_max_f32_e32 v37, v36, v37
	v_sub_f32_e32 v2, v2, v37
	v_sub_f32_e32 v18, v18, v37
	v_sub_f32_e32 v3, v3, v37
	v_sub_f32_e32 v19, v19, v37
	v_sub_f32_e32 v4, v4, v37
	v_sub_f32_e32 v20, v20, v37
	v_sub_f32_e32 v5, v5, v37
	v_sub_f32_e32 v21, v21, v37
	v_sub_f32_e32 v6, v6, v37
	v_sub_f32_e32 v22, v22, v37
	v_sub_f32_e32 v7, v7, v37
	v_sub_f32_e32 v23, v23, v37
	v_sub_f32_e32 v8, v8, v37
	v_sub_f32_e32 v24, v24, v37
	v_sub_f32_e32 v9, v9, v37
	v_sub_f32_e32 v25, v25, v37
	v_sub_f32_e32 v10, v10, v37
	v_sub_f32_e32 v26, v26, v37
	v_sub_f32_e32 v11, v11, v37
	v_sub_f32_e32 v27, v27, v37
	v_sub_f32_e32 v12, v12, v37
	v_sub_f32_e32 v28, v28, v37
	v_sub_f32_e32 v13, v13, v37
	v_sub_f32_e32 v29, v29, v37
	v_sub_f32_e32 v14, v14, v37
	v_sub_f32_e32 v30, v30, v37
	v_sub_f32_e32 v15, v15, v37
	v_sub_f32_e32 v31, v31, v37
	v_sub_f32_e32 v16, v16, v37
	v_sub_f32_e32 v32, v32, v37
	v_sub_f32_e32 v17, v17, v37
	v_sub_f32_e32 v33, v33, v37
	v_exp_f32_e32 v52, v2
	v_exp_f32_e32 v53, v18
	v_exp_f32_e32 v54, v3
	v_exp_f32_e32 v55, v19
	v_exp_f32_e32 v56, v4
	v_exp_f32_e32 v57, v20
	v_exp_f32_e32 v58, v5
	v_exp_f32_e32 v59, v21
	v_exp_f32_e32 v60, v6
	v_exp_f32_e32 v61, v22
	v_exp_f32_e32 v62, v7
	v_exp_f32_e32 v63, v23
	v_exp_f32_e32 v64, v8
	v_exp_f32_e32 v65, v24
	v_exp_f32_e32 v101, v9
	v_exp_f32_e32 v102, v25
	v_exp_f32_e32 v103, v10
	v_exp_f32_e32 v104, v26
	v_exp_f32_e32 v114, v27
	v_exp_f32_e32 v105, v11
	v_exp_f32_e32 v107, v12
	v_exp_f32_e32 v115, v28
	v_exp_f32_e32 v108, v13
	v_exp_f32_e32 v116, v29
	v_exp_f32_e32 v109, v14
	v_exp_f32_e32 v117, v30
	ds_read_b128 v[10:13], v35 offset:16384
	v_exp_f32_e32 v118, v15
	v_exp_f32_e32 v119, v31
	ds_read_b128 v[2:5], v35 offset:20480
	v_exp_f32_e32 v35, v16
	v_exp_f32_e32 v120, v32
	ds_read_b128 v[6:9], v48 offset:16384
	v_exp_f32_e32 v121, v17
	v_exp_f32_e32 v122, v33
	ds_read_b128 v[14:17], v48 offset:20480
	ds_read_b128 v[18:21], v49 offset:16384
	ds_read_b128 v[22:25], v49 offset:20480
	ds_read_b128 v[26:29], v50 offset:16384
	ds_read_b128 v[30:33], v50 offset:20480
	v_add_f32_e32 v36, 0, v52
	v_add_f32_e32 v36, v53, v36
	v_add_f32_e32 v36, v54, v36
	v_add_f32_e32 v36, v55, v36
	v_add_f32_e32 v36, v56, v36
	v_add_f32_e32 v36, v57, v36
	v_add_f32_e32 v36, v58, v36
	v_add_f32_e32 v36, v59, v36
	v_add_f32_e32 v36, v60, v36
	v_add_f32_e32 v36, v61, v36
	v_add_f32_e32 v36, v62, v36
	v_add_f32_e32 v36, v63, v36
	v_add_f32_e32 v36, v64, v36
	v_add_f32_e32 v36, v65, v36
	v_add_f32_e32 v36, v101, v36
	v_add_f32_e32 v36, v102, v36
	v_add_f32_e32 v36, v103, v36
	v_add_f32_e32 v36, v104, v36
	v_add_f32_e32 v36, v105, v36
	v_add_f32_e32 v36, v114, v36
	v_add_f32_e32 v36, v107, v36
	v_add_f32_e32 v36, v115, v36
	v_add_f32_e32 v36, v108, v36
	v_add_f32_e32 v36, v116, v36
	v_add_f32_e32 v36, v109, v36
	v_add_f32_e32 v36, v117, v36
	v_add_f32_e32 v36, v118, v36
	v_add_f32_e32 v36, v119, v36
	v_add_f32_e32 v36, v35, v36
	v_add_f32_e32 v36, v120, v36
	v_add_f32_e32 v36, v121, v36
	v_add_f32_e32 v36, v122, v36
	v_sub_u32_e32 v82, v34, v38
	v_pk_add_f32 v[198:199], v[36:37], 0 op_sel_hi:[1,0]
	v_add_u32_e32 v36, -1, v82
	v_add_u32_e32 v37, -3, v82
	v_add_u32_e32 v38, -2, v82
	v_add_u32_e32 v39, -5, v82
	v_add_u32_e32 v40, -4, v82
	v_add_u32_e32 v41, -7, v82
	v_add_u32_e32 v42, -6, v82
	v_subrev_u32_e32 v43, 17, v82
	v_add_u32_e32 v44, -16, v82
	v_subrev_u32_e32 v45, 19, v82
	v_subrev_u32_e32 v46, 18, v82
	v_subrev_u32_e32 v47, 21, v82
	v_subrev_u32_e32 v48, 20, v82
	v_subrev_u32_e32 v49, 23, v82
	v_subrev_u32_e32 v50, 22, v82
	v_cvt_f32_i32_e32 v50, v50
	v_cvt_f32_i32_e32 v51, v49
	v_cvt_f32_i32_e32 v48, v48
	v_cvt_f32_i32_e32 v49, v47
	v_cvt_f32_i32_e32 v46, v46
	v_cvt_f32_i32_e32 v47, v45
	v_cvt_f32_i32_e32 v44, v44
	v_cvt_f32_i32_e32 v45, v43
	v_cvt_f32_i32_e32 v42, v42
	v_cvt_f32_i32_e32 v43, v41
	v_cvt_f32_i32_e32 v40, v40
	v_cvt_f32_i32_e32 v41, v39
	v_cvt_f32_i32_e32 v39, v82
	v_cvt_f32_i32_e32 v66, v36
	v_cvt_f32_i32_e32 v67, v37
	v_cvt_f32_i32_e32 v38, v38
	v_and_b32_e32 v36, 0x7fffffff, v39
	v_and_b32_e32 v37, 0x7fffffff, v66
	v_and_b32_e32 v39, 0x7fffffff, v67
	v_and_b32_e32 v38, 0x7fffffff, v38
	v_and_b32_e32 v41, 0x7fffffff, v41
	v_and_b32_e32 v40, 0x7fffffff, v40
	v_and_b32_e32 v43, 0x7fffffff, v43
	v_and_b32_e32 v42, 0x7fffffff, v42
	v_and_b32_e32 v45, 0x7fffffff, v45
	v_and_b32_e32 v44, 0x7fffffff, v44
	v_and_b32_e32 v47, 0x7fffffff, v47
	v_and_b32_e32 v46, 0x7fffffff, v46
	v_and_b32_e32 v49, 0x7fffffff, v49
	v_and_b32_e32 v48, 0x7fffffff, v48
	v_and_b32_e32 v51, 0x7fffffff, v51
	v_and_b32_e32 v50, 0x7fffffff, v50
	v_pk_fma_f32 v[80:81], v[0:1], v[50:51], v[198:199] op_sel:[0,0,1] op_sel_hi:[0,1,1] neg_lo:[1,0,1] neg_hi:[1,0,1]
	v_pk_fma_f32 v[78:79], v[0:1], v[48:49], v[198:199] op_sel:[0,0,1] op_sel_hi:[0,1,1] neg_lo:[1,0,1] neg_hi:[1,0,1]
	v_pk_fma_f32 v[76:77], v[0:1], v[46:47], v[198:199] op_sel:[0,0,1] op_sel_hi:[0,1,1] neg_lo:[1,0,1] neg_hi:[1,0,1]
	v_pk_fma_f32 v[74:75], v[0:1], v[44:45], v[198:199] op_sel:[0,0,1] op_sel_hi:[0,1,1] neg_lo:[1,0,1] neg_hi:[1,0,1]
	v_pk_fma_f32 v[72:73], v[0:1], v[42:43], v[198:199] op_sel:[0,0,1] op_sel_hi:[0,1,1] neg_lo:[1,0,1] neg_hi:[1,0,1]
	v_pk_fma_f32 v[70:71], v[0:1], v[40:41], v[198:199] op_sel:[0,0,1] op_sel_hi:[0,1,1] neg_lo:[1,0,1] neg_hi:[1,0,1]
	v_pk_fma_f32 v[68:69], v[0:1], v[38:39], v[198:199] op_sel:[0,0,1] op_sel_hi:[0,1,1] neg_lo:[1,0,1] neg_hi:[1,0,1]
	v_pk_fma_f32 v[66:67], v[0:1], v[36:37], v[198:199] op_sel:[0,0,1] op_sel_hi:[0,1,1] neg_lo:[1,0,1] neg_hi:[1,0,1]
	v_subrev_u32_e32 v36, 33, v82
	v_subrev_u32_e32 v37, 32, v82
	v_subrev_u32_e32 v38, 35, v82
	v_subrev_u32_e32 v39, 34, v82
	v_subrev_u32_e32 v40, 37, v82
	v_subrev_u32_e32 v41, 36, v82
	v_subrev_u32_e32 v42, 39, v82
	v_subrev_u32_e32 v43, 38, v82
	v_subrev_u32_e32 v44, 49, v82
	v_subrev_u32_e32 v45, 48, v82
	v_subrev_u32_e32 v46, 51, v82
	v_subrev_u32_e32 v47, 50, v82
	v_subrev_u32_e32 v48, 53, v82
	v_subrev_u32_e32 v49, 52, v82
	v_subrev_u32_e32 v50, 55, v82
	v_subrev_u32_e32 v51, 54, v82
	v_cvt_f32_i32_e32 v82, v51
	v_cvt_f32_i32_e32 v50, v50
	v_cvt_f32_i32_e32 v51, v49
	v_cvt_f32_i32_e32 v48, v48
	v_cvt_f32_i32_e32 v49, v47
	v_cvt_f32_i32_e32 v46, v46
	v_cvt_f32_i32_e32 v47, v45
	v_cvt_f32_i32_e32 v44, v44
	v_cvt_f32_i32_e32 v45, v43
	v_cvt_f32_i32_e32 v42, v42
	v_cvt_f32_i32_e32 v43, v41
	v_cvt_f32_i32_e32 v40, v40
	v_cvt_f32_i32_e32 v36, v36
	v_cvt_f32_i32_e32 v41, v37
	v_cvt_f32_i32_e32 v38, v38
	v_cvt_f32_i32_e32 v83, v39
	v_and_b32_e32 v37, 0x7fffffff, v36
	v_and_b32_e32 v36, 0x7fffffff, v41
	v_and_b32_e32 v39, 0x7fffffff, v38
	v_and_b32_e32 v38, 0x7fffffff, v83
	v_and_b32_e32 v41, 0x7fffffff, v40
	v_and_b32_e32 v40, 0x7fffffff, v43
	v_and_b32_e32 v43, 0x7fffffff, v42
	v_and_b32_e32 v42, 0x7fffffff, v45
	v_and_b32_e32 v45, 0x7fffffff, v44
	v_and_b32_e32 v44, 0x7fffffff, v47
	v_and_b32_e32 v47, 0x7fffffff, v46
	v_and_b32_e32 v46, 0x7fffffff, v49
	v_and_b32_e32 v49, 0x7fffffff, v48
	v_and_b32_e32 v48, 0x7fffffff, v51
	v_and_b32_e32 v51, 0x7fffffff, v50
	v_and_b32_e32 v50, 0x7fffffff, v82
	v_pk_fma_f32 v[96:97], v[0:1], v[50:51], v[198:199] op_sel:[0,0,1] op_sel_hi:[0,1,1] neg_lo:[1,0,1] neg_hi:[1,0,1]
	v_pk_fma_f32 v[94:95], v[0:1], v[48:49], v[198:199] op_sel:[0,0,1] op_sel_hi:[0,1,1] neg_lo:[1,0,1] neg_hi:[1,0,1]
	v_pk_fma_f32 v[92:93], v[0:1], v[46:47], v[198:199] op_sel:[0,0,1] op_sel_hi:[0,1,1] neg_lo:[1,0,1] neg_hi:[1,0,1]
	v_pk_fma_f32 v[90:91], v[0:1], v[44:45], v[198:199] op_sel:[0,0,1] op_sel_hi:[0,1,1] neg_lo:[1,0,1] neg_hi:[1,0,1]
	v_pk_fma_f32 v[88:89], v[0:1], v[42:43], v[198:199] op_sel:[0,0,1] op_sel_hi:[0,1,1] neg_lo:[1,0,1] neg_hi:[1,0,1]
	v_pk_fma_f32 v[86:87], v[0:1], v[40:41], v[198:199] op_sel:[0,0,1] op_sel_hi:[0,1,1] neg_lo:[1,0,1] neg_hi:[1,0,1]
	v_pk_fma_f32 v[84:85], v[0:1], v[38:39], v[198:199] op_sel:[0,0,1] op_sel_hi:[0,1,1] neg_lo:[1,0,1] neg_hi:[1,0,1]
	v_pk_fma_f32 v[82:83], v[0:1], v[36:37], v[198:199] op_sel:[0,0,1] op_sel_hi:[0,1,1] neg_lo:[1,0,1] neg_hi:[1,0,1]
	s_waitcnt lgkmcnt(0)
	v_mfma_f32_32x32x16_bf16 v[66:81], v[10:13], v[130:133], v[66:81]
	v_cvt_pk_bf16_f32 v98, v52, v54
	v_cvt_pk_bf16_f32 v99, v56, v58
	v_cvt_pk_bf16_f32 v100, v60, v62
	v_cvt_pk_bf16_f32 v101, v64, v101
	v_cvt_pk_bf16_f32 v110, v53, v55
	v_cvt_pk_bf16_f32 v111, v57, v59
	v_cvt_pk_bf16_f32 v112, v61, v63
	v_mfma_f32_32x32x16_bf16 v[82:97], v[2:5], v[130:133], v[82:97]
	v_cvt_pk_bf16_f32 v113, v65, v102
	v_cvt_pk_bf16_f32 v106, v103, v105
	v_cvt_pk_bf16_f32 v107, v107, v108
	v_cvt_pk_bf16_f32 v108, v109, v118
	v_cvt_pk_bf16_f32 v109, v35, v121
	v_cvt_pk_bf16_f32 v114, v104, v114
	v_cvt_pk_bf16_f32 v115, v115, v116
	v_mfma_f32_32x32x16_bf16 v[66:81], v[6:9], v[134:137], v[66:81]
	v_cvt_pk_bf16_f32 v116, v117, v119
	s_cmp_lt_i32 s48, 2
	v_cvt_pk_bf16_f32 v117, v120, v122
	v_mfma_f32_32x32x16_bf16 v[82:97], v[14:17], v[134:137], v[82:97]
	v_mfma_f32_32x32x16_bf16 v[66:81], v[18:21], v[138:141], v[66:81]
	v_mfma_f32_32x32x16_bf16 v[82:97], v[22:25], v[138:141], v[82:97]
	v_mfma_f32_32x32x16_bf16 v[66:81], v[26:29], v[142:145], v[66:81]
	v_mfma_f32_32x32x16_bf16 v[82:97], v[30:33], v[142:145], v[82:97]
	s_cbranch_scc1 .LBB0_472
	v_sub_u32_e32 v0, v148, v34
	v_cvt_f32_i32_e32 v155, v0
	v_mov_b32_e32 v16, v153
	v_mov_b32_e32 v17, v153
	v_mov_b32_e32 v2, v153
	v_mov_b32_e32 v3, v153
	v_mov_b32_e32 v4, v153
	v_mov_b32_e32 v5, v153
	v_mov_b32_e32 v6, v153
	v_mov_b32_e32 v7, v153
	v_mov_b32_e32 v8, v153
	v_mov_b32_e32 v9, v153
	v_mov_b32_e32 v10, v153
	v_mov_b32_e32 v11, v153
	v_mov_b32_e32 v12, v153
	v_mov_b32_e32 v13, v153
	v_mov_b32_e32 v14, v153
	v_mov_b32_e32 v15, v153
	v_mov_b64_e32 v[32:33], v[16:17]
	v_mov_b64_e32 v[48:49], v[16:17]
	v_mov_b64_e32 v[64:65], v[16:17]
	s_mov_b64 s[2:3], 0
	v_mov_b32_e32 v0, 1.0
	s_mov_b32 s62, 2
	s_mov_b32 s34, 5
	v_mov_b64_e32 v[30:31], v[14:15]
	v_mov_b64_e32 v[28:29], v[12:13]
	v_mov_b64_e32 v[26:27], v[10:11]
	v_mov_b64_e32 v[24:25], v[8:9]
	v_mov_b64_e32 v[22:23], v[6:7]
	v_mov_b64_e32 v[20:21], v[4:5]
	v_mov_b64_e32 v[18:19], v[2:3]
	v_mov_b64_e32 v[46:47], v[14:15]
	v_mov_b64_e32 v[44:45], v[12:13]
	v_mov_b64_e32 v[42:43], v[10:11]
	v_mov_b64_e32 v[40:41], v[8:9]
	v_mov_b64_e32 v[38:39], v[6:7]
	v_mov_b64_e32 v[36:37], v[4:5]
	v_mov_b64_e32 v[34:35], v[2:3]
	v_mov_b64_e32 v[62:63], v[14:15]
	v_mov_b64_e32 v[60:61], v[12:13]
	v_mov_b64_e32 v[58:59], v[10:11]
	v_mov_b64_e32 v[56:57], v[8:9]
	v_mov_b64_e32 v[54:55], v[6:7]
	v_mov_b64_e32 v[52:53], v[4:5]
	v_mov_b64_e32 v[50:51], v[2:3]
	s_mov_b32 s81, 0
	s_mov_b32 s83, 0
	s_mov_b32 s85, 0
	s_add_i32 s61, s34, -2
	s_cmp_gt_i32 s61, s48
	s_mov_b64 s[4:5], -1
	s_cbranch_scc0 .LBB0_468
